# sample rows output projection split-K units and final norm pass also handed out as attention-phase tickets (release-acquire counters chain them); phase 4b ends the kernel: no split-K tail, no sixth gr
# speedup vs baseline: 1.1152x; 1.0112x over previous
.LBB0_474:
	s_andn2_b64 vcc, exec, s[8:9]
	s_cbranch_vccnz .LBB0_477
	s_barrier
	v_mov_b32_e32 v0, 0xf000
	ds_read_b32 v0, v0
	s_waitcnt lgkmcnt(0)
	v_readfirstlane_b32 s14, v0
	s_bfe_u32 s11, s83, 0x10001
	s_cmpk_lt_u32 s14, 0x116
	s_cselect_b64 s[6:7], -1, 0
	s_and_b64 vcc, exec, s[6:7]
	s_cbranch_vccz .Lq_done
	s_cmp_lt_u32 s14, 4
	s_cbranch_scc0 .Lq_nottiny
	s_lshl_b32 s11, s11, 8
	s_or_b32 s14, s14, s11
	s_branch .Lq_done

.Lq_notsmp:
	s_add_i32 s14, s14, -8
	s_cmpk_lt_u32 s14, 0x80
	s_cbranch_scc1 .Lq_prompt
	s_cmpk_lt_u32 s14, 0x82
	s_cbranch_scc0 .Lq_r2
	s_addk_i32 s14, 0xff80
	s_lshl_b32 s10, s11, 1
	s_add_i32 s100, s14, s10
	s_branch .Le4a_call
.Lq_r2:
	s_cmpk_lt_u32 s14, 0xc6
	s_cbranch_scc0 .Lq_r3
	s_add_i32 s14, s14, -2
	s_branch .Lq_prompt
.Lq_r3:
	s_cmpk_lt_u32 s14, 0xce
	s_cbranch_scc0 .Lq_r4
	s_addk_i32 s14, 0xff3a
	s_lshl_b32 s10, s11, 3
	s_add_i32 s100, s14, s10
	s_branch .Lz_call
.Lq_r4:
	s_cmpk_lt_u32 s14, 0xf6
	s_cbranch_scc0 .Lq_r5
	s_add_i32 s14, s14, -10
	s_branch .Lq_prompt
.Lq_r5:
	s_cmpk_lt_u32 s14, 0xfe
	s_cbranch_scc0 .Lq_r6
	s_addk_i32 s14, 0xff0a
	s_lshl_b32 s10, s11, 3
	s_add_i32 s100, s14, s10
	s_branch .Lf_call
.Lq_r6:
	s_add_i32 s14, s14, -18

.Le4a_return:
	s_mov_b32 s101, 0
	v_mbcnt_lo_u32_b32 v214, -1, 0
	s_waitcnt vmcnt(0)
	s_barrier
	s_and_saveexec_b64 s[6:7], s[80:81]
	s_cbranch_execz .Le4a_counted
	buffer_wbl2 sc1
	s_waitcnt vmcnt(0)
	v_mov_b32_e32 v2, 0x3a00
	v_mov_b32_e32 v3, 1
	global_atomic_add v2, v3, s[78:79]
.Le4a_counted:
	s_or_b64 exec, exec, s[6:7]
	s_branch .Lp3_setup
.Lz_call:
	s_and_saveexec_b64 s[6:7], s[80:81]
	s_cbranch_execz .Lz_ready
	v_mov_b32_e32 v2, 0x3a00
.Lz_poll:
	global_load_dword v3, v2, s[78:79] sc1
	s_waitcnt vmcnt(0)
	v_cmp_gt_u32_e32 vcc, 4, v3
	s_cbranch_vccz .Lz_ready
	s_sleep 1
	s_branch .Lz_poll
.Lz_ready:
	s_or_b64 exec, exec, s[6:7]
	s_barrier
	buffer_inv sc1
	s_waitcnt vmcnt(0)
	s_mov_b32 s101, 2
	s_mov_b32 s98, s86
	s_mov_b32 s86, s100
	s_lshl_b32 s63, s100, 8
	s_add_u32 s4, s38, 0x55c0000
	s_addc_u32 s5, s39, 0
	v_mov_b32_e32 v140, v218
	v_ashrrev_i32_e32 v135, 2, v218
	v_and_b32_e32 v134, 15, v218
	v_bfe_u32 v132, v218, 6, 2
	v_lshlrev_b32_e32 v132, 7, v132
	s_branch .Lz_entry
.Lz_return:
	s_mov_b32 s86, s98
	s_mov_b32 s101, 0
	v_mbcnt_lo_u32_b32 v214, -1, 0
	s_waitcnt vmcnt(0)
	s_barrier
	s_and_saveexec_b64 s[6:7], s[80:81]
	s_cbranch_execz .Lz_counted
	v_mov_b32_e32 v2, 0x3b00
	v_mov_b32_e32 v3, 1
	global_atomic_add v2, v3, s[78:79]

.Lf_call:
	s_and_saveexec_b64 s[6:7], s[80:81]
	s_cbranch_execz .Lf_ready
	v_mov_b32_e32 v2, 0x3b00
.Lf_poll:
	global_load_dword v3, v2, s[78:79] sc1
	s_waitcnt vmcnt(0)
	v_cmp_gt_u32_e32 vcc, 16, v3
	s_cbranch_vccz .Lf_ready
	s_sleep 1
	s_branch .Lf_poll
.Lf_ready:
	s_or_b64 exec, exec, s[6:7]
	s_barrier
	buffer_inv sc1
	s_waitcnt vmcnt(0)
	s_load_dwordx4 s[8:11], s[0:1], 0x80
	s_mov_b64 s[98:99], s[0:1]
	s_mov_b32 s101, 3
	s_waitcnt lgkmcnt(0)
	s_branch .Lf_entry
.Lf_return:
	s_mov_b64 exec, -1
	s_mov_b64 s[0:1], s[98:99]
	s_mov_b32 s101, 0
	v_mbcnt_lo_u32_b32 v214, -1, 0
	s_waitcnt vmcnt(0)
	s_barrier
	s_branch .Lp3_setup

.LBB0_609:
	v_add_u32_e32 v10, -4, v128
	v_ashrrev_i32_e32 v11, 31, v10
	v_add_u32_e32 v1, s6, v136
	v_lshl_add_u64 v[12:13], v[10:11], 2, s[2:3]
	ds_read_b128 v[2:5], v1
	ds_read_b128 v[6:9], v1 offset:16
	global_load_dword v38, v[12:13], off sc1
	v_lshlrev_b64 v[26:27], 12, v[10:11]
	v_lshl_add_u64 v[28:29], v[66:67], 0, v[26:27]
	global_load_dwordx4 v[10:13], v[64:65], off offset:16
	global_load_dwordx4 v[14:17], v[64:65], off
	global_load_dwordx4 v[18:21], v[28:29], off
	global_load_dwordx4 v[22:25], v[28:29], off offset:16
	v_lshl_add_u64 v[36:37], v[68:69], 0, v[26:27]
	ds_read_b128 v[26:29], v1 offset:4160
	ds_read_b128 v[30:33], v1 offset:4176
	v_ashrrev_i32_e32 v129, 31, v128
	v_lshl_add_u64 v[34:35], v[128:129], 2, s[2:3]
	s_addk_i32 s6, 0x2080
	s_cmpk_lg_u32 s6, 0x8200
	s_waitcnt vmcnt(4)
	v_fmamk_f32 v1, v38, 0x3a800000, v0
	v_mul_f32_e32 v38, 0x4b800000, v1
	v_cmp_gt_f32_e32 vcc, s7, v1
	s_nop 1
	v_cndmask_b32_e32 v1, v1, v38, vcc
	v_rsq_f32_e32 v1, v1
	s_nop 0
	v_mul_f32_e32 v38, 0x45800000, v1
	v_cndmask_b32_e32 v38, v1, v38, vcc
	s_waitcnt lgkmcnt(3)
	v_pk_mul_f32 v[2:3], v[2:3], v[38:39] op_sel_hi:[1,0]
	v_pk_mul_f32 v[4:5], v[4:5], v[38:39] op_sel_hi:[1,0]
	s_waitcnt lgkmcnt(2)
	v_pk_mul_f32 v[6:7], v[6:7], v[38:39] op_sel_hi:[1,0]
	v_pk_mul_f32 v[8:9], v[8:9], v[38:39] op_sel_hi:[1,0]
	s_waitcnt vmcnt(1)
	v_pk_fma_f32 v[4:5], v[16:17], v[4:5], v[20:21]
	v_pk_fma_f32 v[2:3], v[14:15], v[2:3], v[18:19]
	s_waitcnt vmcnt(0)
	v_pk_fma_f32 v[8:9], v[12:13], v[8:9], v[24:25]
	v_pk_fma_f32 v[6:7], v[10:11], v[6:7], v[22:23]
	global_store_dwordx4 v[36:37], v[2:5], off
	global_store_dwordx4 v[36:37], v[6:9], off offset:16
	global_load_dword v1, v[34:35], off sc1
	v_lshlrev_b64 v[18:19], 12, v[128:129]
	v_lshl_add_u64 v[20:21], v[66:67], 0, v[18:19]
	global_load_dwordx4 v[2:5], v[64:65], off
	global_load_dwordx4 v[6:9], v[20:21], off
	global_load_dwordx4 v[10:13], v[20:21], off offset:16
	global_load_dwordx4 v[14:17], v[64:65], off offset:16
	v_add_u32_e32 v128, 8, v128
	v_lshl_add_u64 v[18:19], v[68:69], 0, v[18:19]
	s_waitcnt vmcnt(4)
	v_fmamk_f32 v1, v1, 0x3a800000, v0
	v_mul_f32_e32 v20, 0x4b800000, v1
	v_cmp_gt_f32_e32 vcc, s7, v1
	s_nop 1
	v_cndmask_b32_e32 v1, v1, v20, vcc
	v_rsq_f32_e32 v1, v1
	s_nop 0
	v_mul_f32_e32 v20, 0x45800000, v1
	v_cndmask_b32_e32 v20, v1, v20, vcc
	s_waitcnt lgkmcnt(1)
	v_pk_mul_f32 v[22:23], v[26:27], v[20:21] op_sel_hi:[1,0]
	v_pk_mul_f32 v[24:25], v[28:29], v[20:21] op_sel_hi:[1,0]
	s_waitcnt lgkmcnt(0)
	v_pk_mul_f32 v[26:27], v[30:31], v[20:21] op_sel_hi:[1,0]
	v_pk_mul_f32 v[20:21], v[32:33], v[20:21] op_sel_hi:[1,0]
	s_waitcnt vmcnt(2)
	v_pk_fma_f32 v[4:5], v[4:5], v[24:25], v[8:9]
	v_pk_fma_f32 v[2:3], v[2:3], v[22:23], v[6:7]
	s_waitcnt vmcnt(0)
	v_pk_fma_f32 v[8:9], v[16:17], v[20:21], v[12:13]
	v_pk_fma_f32 v[6:7], v[14:15], v[26:27], v[10:11]
	global_store_dwordx4 v[18:19], v[2:5], off
	global_store_dwordx4 v[18:19], v[6:9], off offset:16
	s_cbranch_scc1 .LBB0_609
	s_branch .LBB0_616
.Lz_entry:
	v_mov_b32_e32 v64, v218
	s_and_b32 s2, s63, 0x300
	v_bfe_i32 v1, v64, 27, 1
	v_lshlrev_b32_e32 v20, 4, v64
	v_lshrrev_b32_e32 v1, 22, v1
	v_add_u32_e32 v1, v20, v1
	v_and_b32_e32 v1, 0xfffffc00, v1
	v_ashrrev_i32_e32 v0, 31, v64
	v_sub_u32_e32 v1, v20, v1
	v_lshrrev_b32_e32 v0, 26, v0
	v_lshrrev_b32_e32 v2, 4, v1
	v_add_u32_e32 v0, v64, v0
	v_bitop3_b32 v2, v2, v1, 32 bitop3:0x6c
	v_ashrrev_i32_e32 v1, 31, v1
	v_ashrrev_i32_e32 v0, 6, v0
	v_lshrrev_b32_e32 v1, 26, v1
	v_lshlrev_b32_e32 v3, 3, v0
	v_add_u32_e32 v1, v2, v1
	v_and_b32_e32 v3, 0x1ffff0, v3
	v_ashrrev_i32_e32 v1, 6, v1
	v_add_u32_e32 v3, v1, v3
	v_mul_i32_i24_e32 v1, 64, v1
	v_lshlrev_b32_e32 v0, 5, v0
	v_sub_u32_e32 v1, v2, v1
	v_mov_b32_e32 v2, 1
	v_and_b32_e32 v0, 32, v0
	v_ashrrev_i16_sdwa v1, v2, sext(v1) dst_sel:DWORD dst_unused:UNUSED_PAD src0_sel:DWORD src1_sel:BYTE_0
	v_bfe_i32 v1, v1, 0, 16
	v_lshl_or_b32 v0, v3, 10, v0
	v_add_lshl_u32 v0, v0, v1, 1
	v_add_u32_e32 v1, 0x2000, v20
	v_ashrrev_i32_e32 v3, 31, v1
	v_lshrrev_b32_e32 v3, 22, v3
	v_add_u32_e32 v3, v1, v3
	v_ashrrev_i32_e32 v3, 10, v3
	v_mul_i32_i24_e32 v4, 0x400, v3
	s_lshl_b32 s2, s2, 1
	v_sub_u32_e32 v1, v1, v4
	s_add_u32 s12, s38, s2
	v_lshrrev_b32_e32 v4, 4, v1
	s_addc_u32 s13, s39, 0
	v_bitop3_b32 v1, v4, v1, 32 bitop3:0x6c
	s_add_u32 s14, s4, s2
	v_ashrrev_i32_e32 v5, 31, v1
	s_addc_u32 s15, s5, 0
	s_lshl_b32 s2, s86, 6
	v_lshrrev_b32_e32 v5, 26, v5
	s_and_b32 s2, s2, 0xffffff00
	v_add_u32_e32 v5, v1, v5
	v_lshlrev_b32_e32 v4, 3, v3
	v_lshrrev_b32_e32 v6, 6, v5
	v_and_b32_e32 v5, 0xc0, v5
	s_ashr_i32 s3, s2, 31
	v_and_b32_e32 v4, 0x1ffff0, v4
	v_lshlrev_b32_e32 v3, 5, v3
	v_sub_u32_e32 v1, v1, v5
	s_lshl_b64 s[4:5], s[2:3], 11
	v_add_u32_e32 v18, s90, v20
	v_add_u32_e32 v4, v6, v4
	v_and_b32_e32 v3, 32, v3
	v_ashrrev_i16_sdwa v1, v2, sext(v1) dst_sel:DWORD dst_unused:UNUSED_PAD src0_sel:DWORD src1_sel:BYTE_0
	s_add_u32 s4, s14, s4
	v_readfirstlane_b32 s6, v18
	v_add_u32_e32 v19, 0x2000, v18
	v_bfe_i32 v1, v1, 0, 16
	v_lshl_or_b32 v2, v4, 10, v3
	s_addc_u32 s5, s15, s5
	s_mov_b32 m0, s6
	v_readfirstlane_b32 s6, v19
	v_add_u32_e32 v14, 0, v20
	v_add_lshl_u32 v2, v2, v1, 1
	s_barrier
	global_load_lds_dwordx4 v0, s[4:5]
	s_mov_b32 m0, s6
	s_add_u32 s6, s12, 0x2000000
	v_readfirstlane_b32 s16, v14
	v_add_u32_e32 v15, 0x2000, v14
	global_load_lds_dwordx4 v2, s[4:5]
	s_addc_u32 s7, s13, 0
	s_mov_b32 m0, s16
	v_readfirstlane_b32 s16, v15
	global_load_lds_dwordx4 v0, s[6:7]
	s_mov_b32 m0, s16
	v_add_u32_e32 v16, s87, v20
	global_load_lds_dwordx4 v2, s[6:7]
	s_or_b32 s6, s2, 0x80
	s_ashr_i32 s7, s6, 31
	s_lshl_b64 s[6:7], s[6:7], 11
	s_add_u32 s6, s14, s6
	v_readfirstlane_b32 s14, v16
	v_add_u32_e32 v17, 0x2000, v16
	s_addc_u32 s7, s15, s7
	s_mov_b32 m0, s14
	v_readfirstlane_b32 s14, v17
	v_add_u32_e32 v12, 0x4000, v14
	global_load_lds_dwordx4 v0, s[6:7]
	s_mov_b32 m0, s14
	s_add_u32 s14, s12, 0x2040000
	v_readfirstlane_b32 s16, v12
	v_add_u32_e32 v13, 0x6000, v14
	global_load_lds_dwordx4 v2, s[6:7]
	s_addc_u32 s15, s13, 0
	s_mov_b32 m0, s16
	v_readfirstlane_b32 s16, v13
	global_load_lds_dwordx4 v0, s[14:15]
	s_mov_b32 m0, s16
	v_mov_b32_e32 v1, 0
	global_load_lds_dwordx4 v2, s[14:15]
	v_ashrrev_i32_e32 v21, 8, v64
	v_mov_b32_e32 v3, v1
	v_lshl_add_u64 v[10:11], s[4:5], 0, v[0:1]
	v_lshl_add_u64 v[8:9], s[4:5], 0, v[2:3]
	v_lshl_add_u64 v[6:7], s[6:7], 0, v[0:1]
	v_lshl_add_u64 v[4:5], s[6:7], 0, v[2:3]
	v_cmp_eq_u32_e32 vcc, 1, v21
	s_and_saveexec_b64 s[6:7], vcc
	s_cbranch_execz .LBB0_613
	s_barrier

.LBB0_616:
	s_cmp_eq_u32 s101, 2
	s_cbranch_scc1 .Lz_return
	s_endpgm
	s_waitcnt vmcnt(0)
	s_waitcnt vmcnt(0)
	s_barrier
	s_and_saveexec_b64 s[2:3], s[80:81]
	s_cbranch_execz .LBB0_633
	s_mov_b64 s[6:7], exec
	s_lshl_b32 s4, s83, 8
	v_mbcnt_lo_u32_b32 v0, s6, 0
	s_add_u32 s4, s78, s4
	v_mbcnt_hi_u32_b32 v0, s7, v0
	s_addc_u32 s5, s79, 0
	v_cmp_eq_u32_e32 vcc, 0, v0
	s_and_saveexec_b64 s[12:13], vcc
	s_cbranch_execz .LBB0_619
	s_bcnt1_i32_b64 s6, s[6:7]
	v_mov_b32_e32 v1, 0x1000
	v_mov_b32_e32 v2, s6
	global_atomic_add v1, v1, v2, s[4:5] sc0

.Lf_entry:
	s_lshl_b32 s2, s100, 3
	v_ashrrev_i32_e32 v0, 6, v218
	s_nop 0
	v_add_u32_e32 v0, s2, v0
	s_movk_i32 s2, 0x80
	v_cmp_gt_i32_e32 vcc, s2, v0
	s_and_saveexec_b64 s[2:3], vcc
	s_cbranch_execz .LBB0_636
	v_and_b32_e32 v2, 64, v197
	v_xor_b32_e32 v1, 1, v197
	v_add_u32_e32 v2, 64, v2
	v_cmp_lt_i32_e32 vcc, v1, v2
	s_load_dwordx2 s[0:1], s[0:1], 0x8
	v_mov_b32_e32 v9, 0
	v_cndmask_b32_e32 v1, v197, v1, vcc
	v_lshlrev_b32_e32 v10, 2, v1
	v_xor_b32_e32 v1, 2, v197
	v_cmp_lt_i32_e32 vcc, v1, v2
	s_mov_b64 s[4:5], 0xead8c00
	s_lshl_b32 s2, s33, 3
	v_cndmask_b32_e32 v1, v197, v1, vcc
	v_lshlrev_b32_e32 v11, 2, v1
	v_xor_b32_e32 v1, 4, v197
	v_cmp_lt_i32_e32 vcc, v1, v2
	v_mov_b32_e32 v16, 0x358637bd
	s_mov_b32 s3, 0x800000
	v_cndmask_b32_e32 v1, v197, v1, vcc
	v_lshlrev_b32_e32 v12, 2, v1
	v_xor_b32_e32 v1, 8, v197
	v_cmp_lt_i32_e32 vcc, v1, v2
	s_nop 1
	v_cndmask_b32_e32 v1, v197, v1, vcc
	v_lshlrev_b32_e32 v13, 2, v1
	v_xor_b32_e32 v1, 16, v197
	v_cmp_lt_i32_e32 vcc, v1, v2
	s_nop 1
	v_cndmask_b32_e32 v1, v197, v1, vcc
	v_lshlrev_b32_e32 v14, 2, v1
	v_xor_b32_e32 v1, 32, v197
	v_cmp_lt_i32_e32 vcc, v1, v2
	s_nop 1
	v_cndmask_b32_e32 v1, v197, v1, vcc
	v_lshlrev_b32_e32 v15, 2, v1
	v_lshlrev_b32_e32 v1, 4, v218
	v_and_b32_e32 v8, 0x3f0, v1
	v_lshl_add_u64 v[2:3], s[8:9], 0, v[8:9]
	v_lshl_add_u64 v[4:5], s[38:39], 0, v[8:9]
	s_waitcnt lgkmcnt(0)
	v_lshl_add_u64 v[6:7], s[0:1], 0, v[8:9]
	v_lshl_add_u64 v[8:9], s[10:11], 0, v[8:9]
	s_mov_b64 s[0:1], 0x4000000
	v_lshl_add_u64 v[4:5], v[4:5], 0, s[4:5]
	v_lshl_add_u64 v[8:9], v[8:9], 0, s[0:1]
	s_mov_b64 s[0:1], 0
	s_movk_i32 s4, 0x7f

.LBB0_636:
	s_cmp_eq_u32 s101, 3
	s_cbranch_scc1 .Lf_return
	s_endpgm
